# input-projection epilogue stores write-through (sc1)
# baseline (speedup 1.0000x reference)
.LBB0_190:
	s_cmp_gt_u32 s62, 7
	s_cbranch_scc0 .LBB0_192
	v_cndmask_b32_e64 v144, v130, v132, s[42:43]
	v_cndmask_b32_e64 v145, v131, v133, s[42:43]
	s_lshl_b32 s0, s64, 8
	v_mov_b32_dpp v144, v144 quad_perm:[2,3,0,1] row_mask:0xf bank_mask:0xf bound_ctrl:1
	v_mov_b32_dpp v145, v145 quad_perm:[2,3,0,1] row_mask:0xf bank_mask:0xf bound_ctrl:1
	v_cndmask_b32_e64 v146, v144, v130, s[42:43]
	v_cndmask_b32_e64 v147, v145, v131, s[42:43]
	v_cndmask_b32_e64 v144, v132, v144, s[42:43]
	v_cndmask_b32_e64 v145, v133, v145, s[42:43]
	s_add_i32 s0, s0, s38
	v_cndmask_b32_e64 v152, v146, v147, s[44:45]
	v_cndmask_b32_e64 v153, v144, v145, s[44:45]
	s_ashr_i32 s66, s0, 5
	v_mov_b32_dpp v152, v152 quad_perm:[1,0,3,2] row_mask:0xf bank_mask:0xf bound_ctrl:1
	v_mov_b32_dpp v153, v153 quad_perm:[1,0,3,2] row_mask:0xf bank_mask:0xf bound_ctrl:1
	s_ashr_i32 s67, s66, 31
	s_lshl_b32 s50, s62, 2
	v_readlane_b32 s0, v255, 34
	v_cndmask_b32_e64 v146, v152, v146, s[44:45]
	v_cndmask_b32_e64 v147, v147, v152, s[44:45]
	v_cndmask_b32_e64 v152, v153, v144, s[44:45]
	v_cndmask_b32_e64 v145, v145, v153, s[44:45]
	v_cndmask_b32_e64 v144, v122, v124, s[42:43]
	v_cndmask_b32_e64 v153, v123, v125, s[42:43]
	s_lshl_b64 s[26:27], s[66:67], 15
	s_add_i32 s0, s0, s50
	v_readlane_b32 s55, v252, 52
	v_mov_b32_dpp v144, v144 quad_perm:[2,3,0,1] row_mask:0xf bank_mask:0xf bound_ctrl:1
	v_mov_b32_dpp v153, v153 quad_perm:[2,3,0,1] row_mask:0xf bank_mask:0xf bound_ctrl:1
	s_add_u32 s30, s55, s26
	v_readlane_b32 s57, v252, 54
	v_cndmask_b32_e64 v154, v144, v122, s[42:43]
	v_cndmask_b32_e64 v155, v153, v123, s[42:43]
	v_cndmask_b32_e64 v144, v124, v144, s[42:43]
	v_cndmask_b32_e64 v153, v125, v153, s[42:43]
	s_addc_u32 s31, s57, s27
	s_lshl_b64 s[26:27], s[0:1], 12
	v_cndmask_b32_e64 v156, v154, v155, s[44:45]
	v_cndmask_b32_e64 v157, v144, v153, s[44:45]
	s_add_u32 s34, s30, s26
	v_mov_b32_dpp v156, v156 quad_perm:[1,0,3,2] row_mask:0xf bank_mask:0xf bound_ctrl:1
	v_mov_b32_dpp v157, v157 quad_perm:[1,0,3,2] row_mask:0xf bank_mask:0xf bound_ctrl:1
	s_addc_u32 s35, s31, s27
	v_cndmask_b32_e64 v154, v156, v154, s[44:45]
	v_cndmask_b32_e64 v155, v155, v156, s[44:45]
	v_cndmask_b32_e64 v156, v157, v144, s[44:45]
	v_cvt_pk_bf16_f32 v144, v146, v147
	v_cvt_pk_bf16_f32 v145, v152, v145
	v_cndmask_b32_e64 v153, v153, v157, s[44:45]
	v_cvt_pk_bf16_f32 v146, v154, v155
	v_cvt_pk_bf16_f32 v147, v156, v153
	global_store_dwordx4 v151, v[144:147], s[34:35] sc1
	v_readlane_b32 s0, v255, 27
	s_add_i32 s0, s0, s50
	v_cndmask_b32_e64 v144, v126, v128, s[42:43]
	v_cndmask_b32_e64 v145, v127, v129, s[42:43]
	s_nop 0
	v_mov_b32_dpp v144, v144 quad_perm:[2,3,0,1] row_mask:0xf bank_mask:0xf bound_ctrl:1
	v_mov_b32_dpp v145, v145 quad_perm:[2,3,0,1] row_mask:0xf bank_mask:0xf bound_ctrl:1
	v_cndmask_b32_e64 v146, v144, v126, s[42:43]
	v_cndmask_b32_e64 v147, v145, v127, s[42:43]
	v_cndmask_b32_e64 v144, v128, v144, s[42:43]
	v_cndmask_b32_e64 v145, v129, v145, s[42:43]
	v_cndmask_b32_e64 v152, v146, v147, s[44:45]
	v_cndmask_b32_e64 v153, v144, v145, s[44:45]
	s_nop 0
	v_mov_b32_dpp v152, v152 quad_perm:[1,0,3,2] row_mask:0xf bank_mask:0xf bound_ctrl:1
	v_mov_b32_dpp v153, v153 quad_perm:[1,0,3,2] row_mask:0xf bank_mask:0xf bound_ctrl:1
	v_cndmask_b32_e64 v146, v152, v146, s[44:45]
	v_cndmask_b32_e64 v147, v147, v152, s[44:45]
	v_cndmask_b32_e64 v152, v153, v144, s[44:45]
	v_cndmask_b32_e64 v145, v145, v153, s[44:45]
	v_cndmask_b32_e64 v144, v114, v116, s[42:43]
	v_cndmask_b32_e64 v153, v115, v117, s[42:43]
	s_nop 0
	v_mov_b32_dpp v144, v144 quad_perm:[2,3,0,1] row_mask:0xf bank_mask:0xf bound_ctrl:1
	v_mov_b32_dpp v153, v153 quad_perm:[2,3,0,1] row_mask:0xf bank_mask:0xf bound_ctrl:1
	v_cndmask_b32_e64 v154, v144, v114, s[42:43]
	v_cndmask_b32_e64 v155, v153, v115, s[42:43]
	v_cndmask_b32_e64 v144, v116, v144, s[42:43]
	v_cndmask_b32_e64 v153, v117, v153, s[42:43]
	v_cndmask_b32_e64 v156, v154, v155, s[44:45]
	v_cndmask_b32_e64 v157, v144, v153, s[44:45]
	s_nop 0
	v_mov_b32_dpp v156, v156 quad_perm:[1,0,3,2] row_mask:0xf bank_mask:0xf bound_ctrl:1
	v_mov_b32_dpp v157, v157 quad_perm:[1,0,3,2] row_mask:0xf bank_mask:0xf bound_ctrl:1
	v_cndmask_b32_e64 v154, v156, v154, s[44:45]
	v_cndmask_b32_e64 v155, v155, v156, s[44:45]
	v_cndmask_b32_e64 v156, v157, v144, s[44:45]
	v_cvt_pk_bf16_f32 v144, v146, v147
	v_cvt_pk_bf16_f32 v145, v152, v145
	v_cndmask_b32_e64 v153, v153, v157, s[44:45]
	v_cvt_pk_bf16_f32 v146, v154, v155
	v_cvt_pk_bf16_f32 v147, v156, v153
	global_store_dwordx4 v151, v[144:147], s[34:35] offset:64 sc1
	s_lshl_b64 s[34:35], s[0:1], 12
	s_add_u32 s50, s30, s34
	v_cndmask_b32_e64 v144, v118, v120, s[42:43]
	v_cndmask_b32_e64 v145, v119, v121, s[42:43]
	s_addc_u32 s51, s31, s35
	v_mov_b32_dpp v144, v144 quad_perm:[2,3,0,1] row_mask:0xf bank_mask:0xf bound_ctrl:1
	v_mov_b32_dpp v145, v145 quad_perm:[2,3,0,1] row_mask:0xf bank_mask:0xf bound_ctrl:1
	v_cndmask_b32_e64 v146, v144, v118, s[42:43]
	v_cndmask_b32_e64 v147, v145, v119, s[42:43]
	v_cndmask_b32_e64 v144, v120, v144, s[42:43]
	v_cndmask_b32_e64 v145, v121, v145, s[42:43]
	v_cndmask_b32_e64 v152, v146, v147, s[44:45]
	v_cndmask_b32_e64 v153, v144, v145, s[44:45]
	s_nop 0
	v_mov_b32_dpp v152, v152 quad_perm:[1,0,3,2] row_mask:0xf bank_mask:0xf bound_ctrl:1
	v_mov_b32_dpp v153, v153 quad_perm:[1,0,3,2] row_mask:0xf bank_mask:0xf bound_ctrl:1
	v_cndmask_b32_e64 v146, v152, v146, s[44:45]
	v_cndmask_b32_e64 v147, v147, v152, s[44:45]
	v_cndmask_b32_e64 v152, v153, v144, s[44:45]
	v_cndmask_b32_e64 v145, v145, v153, s[44:45]
	v_cndmask_b32_e64 v144, v102, v104, s[42:43]
	v_cndmask_b32_e64 v153, v103, v105, s[42:43]
	s_nop 0
	v_mov_b32_dpp v144, v144 quad_perm:[2,3,0,1] row_mask:0xf bank_mask:0xf bound_ctrl:1
	v_mov_b32_dpp v153, v153 quad_perm:[2,3,0,1] row_mask:0xf bank_mask:0xf bound_ctrl:1
	v_cndmask_b32_e64 v154, v144, v102, s[42:43]
	v_cndmask_b32_e64 v155, v153, v103, s[42:43]
	v_cndmask_b32_e64 v144, v104, v144, s[42:43]
	v_cndmask_b32_e64 v153, v105, v153, s[42:43]
	v_cndmask_b32_e64 v156, v154, v155, s[44:45]
	v_cndmask_b32_e64 v157, v144, v153, s[44:45]
	s_nop 0
	v_mov_b32_dpp v156, v156 quad_perm:[1,0,3,2] row_mask:0xf bank_mask:0xf bound_ctrl:1
	v_mov_b32_dpp v157, v157 quad_perm:[1,0,3,2] row_mask:0xf bank_mask:0xf bound_ctrl:1
	v_cndmask_b32_e64 v154, v156, v154, s[44:45]
	v_cndmask_b32_e64 v155, v155, v156, s[44:45]
	v_cndmask_b32_e64 v156, v157, v144, s[44:45]
	v_cvt_pk_bf16_f32 v144, v146, v147
	v_cvt_pk_bf16_f32 v145, v152, v145
	v_cndmask_b32_e64 v153, v153, v157, s[44:45]
	v_cvt_pk_bf16_f32 v146, v154, v155
	v_cvt_pk_bf16_f32 v147, v156, v153
	global_store_dwordx4 v151, v[144:147], s[50:51] sc1
	s_nop 1
	v_cndmask_b32_e64 v144, v110, v112, s[42:43]
	v_cndmask_b32_e64 v145, v111, v113, s[42:43]
	s_nop 0
	v_mov_b32_dpp v144, v144 quad_perm:[2,3,0,1] row_mask:0xf bank_mask:0xf bound_ctrl:1
	v_mov_b32_dpp v145, v145 quad_perm:[2,3,0,1] row_mask:0xf bank_mask:0xf bound_ctrl:1
	v_cndmask_b32_e64 v146, v144, v110, s[42:43]
	v_cndmask_b32_e64 v147, v145, v111, s[42:43]
	v_cndmask_b32_e64 v144, v112, v144, s[42:43]
	v_cndmask_b32_e64 v145, v113, v145, s[42:43]
	v_cndmask_b32_e64 v152, v146, v147, s[44:45]
	v_cndmask_b32_e64 v153, v144, v145, s[44:45]
	s_nop 0
	v_mov_b32_dpp v152, v152 quad_perm:[1,0,3,2] row_mask:0xf bank_mask:0xf bound_ctrl:1
	v_mov_b32_dpp v153, v153 quad_perm:[1,0,3,2] row_mask:0xf bank_mask:0xf bound_ctrl:1
	v_cndmask_b32_e64 v146, v152, v146, s[44:45]
	v_cndmask_b32_e64 v147, v147, v152, s[44:45]
	v_cndmask_b32_e64 v152, v153, v144, s[44:45]
	v_cndmask_b32_e64 v145, v145, v153, s[44:45]
	v_cndmask_b32_e64 v144, v94, v96, s[42:43]
	v_cndmask_b32_e64 v153, v95, v97, s[42:43]
	s_nop 0
	v_mov_b32_dpp v144, v144 quad_perm:[2,3,0,1] row_mask:0xf bank_mask:0xf bound_ctrl:1
	v_mov_b32_dpp v153, v153 quad_perm:[2,3,0,1] row_mask:0xf bank_mask:0xf bound_ctrl:1
	v_cndmask_b32_e64 v154, v144, v94, s[42:43]
	v_cndmask_b32_e64 v155, v153, v95, s[42:43]
	v_cndmask_b32_e64 v144, v96, v144, s[42:43]
	v_cndmask_b32_e64 v153, v97, v153, s[42:43]
	v_cndmask_b32_e64 v156, v154, v155, s[44:45]
	v_cndmask_b32_e64 v157, v144, v153, s[44:45]
	s_nop 0
	v_mov_b32_dpp v156, v156 quad_perm:[1,0,3,2] row_mask:0xf bank_mask:0xf bound_ctrl:1
	v_mov_b32_dpp v157, v157 quad_perm:[1,0,3,2] row_mask:0xf bank_mask:0xf bound_ctrl:1
	v_cndmask_b32_e64 v154, v156, v154, s[44:45]
	v_cndmask_b32_e64 v155, v155, v156, s[44:45]
	v_cndmask_b32_e64 v156, v157, v144, s[44:45]
	v_cvt_pk_bf16_f32 v144, v146, v147
	v_cvt_pk_bf16_f32 v145, v152, v145
	v_cndmask_b32_e64 v153, v153, v157, s[44:45]
	v_cvt_pk_bf16_f32 v146, v154, v155
	v_cvt_pk_bf16_f32 v147, v156, v153
	global_store_dwordx4 v151, v[144:147], s[50:51] offset:64 sc1
	s_or_b32 s50, s66, 1
	s_ashr_i32 s51, s50, 31
	v_cndmask_b32_e64 v144, v106, v108, s[42:43]
	v_cndmask_b32_e64 v145, v107, v109, s[42:43]
	s_lshl_b64 s[50:51], s[50:51], 15
	v_mov_b32_dpp v144, v144 quad_perm:[2,3,0,1] row_mask:0xf bank_mask:0xf bound_ctrl:1
	v_mov_b32_dpp v145, v145 quad_perm:[2,3,0,1] row_mask:0xf bank_mask:0xf bound_ctrl:1
	v_cndmask_b32_e64 v146, v144, v106, s[42:43]
	v_cndmask_b32_e64 v147, v145, v107, s[42:43]
	v_cndmask_b32_e64 v144, v108, v144, s[42:43]
	v_cndmask_b32_e64 v145, v109, v145, s[42:43]
	v_cndmask_b32_e64 v152, v146, v147, s[44:45]
	v_cndmask_b32_e64 v153, v144, v145, s[44:45]
	s_add_u32 s0, s55, s50
	v_mov_b32_dpp v152, v152 quad_perm:[1,0,3,2] row_mask:0xf bank_mask:0xf bound_ctrl:1
	v_mov_b32_dpp v153, v153 quad_perm:[1,0,3,2] row_mask:0xf bank_mask:0xf bound_ctrl:1
	v_cndmask_b32_e64 v146, v152, v146, s[44:45]
	v_cndmask_b32_e64 v147, v147, v152, s[44:45]
	v_cndmask_b32_e64 v152, v153, v144, s[44:45]
	v_cndmask_b32_e64 v145, v145, v153, s[44:45]
	v_cndmask_b32_e64 v144, v86, v88, s[42:43]
	v_cndmask_b32_e64 v153, v87, v89, s[42:43]
	s_addc_u32 s55, s57, s51
	v_mov_b32_dpp v144, v144 quad_perm:[2,3,0,1] row_mask:0xf bank_mask:0xf bound_ctrl:1
	v_mov_b32_dpp v153, v153 quad_perm:[2,3,0,1] row_mask:0xf bank_mask:0xf bound_ctrl:1
	v_cndmask_b32_e64 v154, v144, v86, s[42:43]
	v_cndmask_b32_e64 v155, v153, v87, s[42:43]
	v_cndmask_b32_e64 v144, v88, v144, s[42:43]
	v_cndmask_b32_e64 v153, v89, v153, s[42:43]
	v_cndmask_b32_e64 v156, v154, v155, s[44:45]
	v_cndmask_b32_e64 v157, v144, v153, s[44:45]
	s_add_u32 s50, s0, s26
	v_mov_b32_dpp v156, v156 quad_perm:[1,0,3,2] row_mask:0xf bank_mask:0xf bound_ctrl:1
	v_mov_b32_dpp v157, v157 quad_perm:[1,0,3,2] row_mask:0xf bank_mask:0xf bound_ctrl:1
	s_addc_u32 s51, s55, s27
	v_cndmask_b32_e64 v154, v156, v154, s[44:45]
	v_cndmask_b32_e64 v155, v155, v156, s[44:45]
	v_cndmask_b32_e64 v156, v157, v144, s[44:45]
	v_cvt_pk_bf16_f32 v144, v146, v147
	v_cvt_pk_bf16_f32 v145, v152, v145
	v_cndmask_b32_e64 v153, v153, v157, s[44:45]
	v_cvt_pk_bf16_f32 v146, v154, v155
	v_cvt_pk_bf16_f32 v147, v156, v153
	global_store_dwordx4 v151, v[144:147], s[50:51] sc1
	s_nop 1
	v_cndmask_b32_e64 v144, v98, v100, s[42:43]
	v_cndmask_b32_e64 v145, v99, v101, s[42:43]
	s_nop 0
	v_mov_b32_dpp v144, v144 quad_perm:[2,3,0,1] row_mask:0xf bank_mask:0xf bound_ctrl:1
	v_mov_b32_dpp v145, v145 quad_perm:[2,3,0,1] row_mask:0xf bank_mask:0xf bound_ctrl:1
	v_cndmask_b32_e64 v146, v144, v98, s[42:43]
	v_cndmask_b32_e64 v147, v145, v99, s[42:43]
	v_cndmask_b32_e64 v144, v100, v144, s[42:43]
	v_cndmask_b32_e64 v145, v101, v145, s[42:43]
	v_cndmask_b32_e64 v152, v146, v147, s[44:45]
	v_cndmask_b32_e64 v153, v144, v145, s[44:45]
	s_nop 0
	v_mov_b32_dpp v152, v152 quad_perm:[1,0,3,2] row_mask:0xf bank_mask:0xf bound_ctrl:1
	v_mov_b32_dpp v153, v153 quad_perm:[1,0,3,2] row_mask:0xf bank_mask:0xf bound_ctrl:1
	v_cndmask_b32_e64 v146, v152, v146, s[44:45]
	v_cndmask_b32_e64 v147, v147, v152, s[44:45]
	v_cndmask_b32_e64 v152, v153, v144, s[44:45]
	v_cndmask_b32_e64 v145, v145, v153, s[44:45]
	v_cndmask_b32_e64 v144, v78, v80, s[42:43]
	v_cndmask_b32_e64 v153, v79, v81, s[42:43]
	s_nop 0
	v_mov_b32_dpp v144, v144 quad_perm:[2,3,0,1] row_mask:0xf bank_mask:0xf bound_ctrl:1
	v_mov_b32_dpp v153, v153 quad_perm:[2,3,0,1] row_mask:0xf bank_mask:0xf bound_ctrl:1
	v_cndmask_b32_e64 v154, v144, v78, s[42:43]
	v_cndmask_b32_e64 v155, v153, v79, s[42:43]
	v_cndmask_b32_e64 v144, v80, v144, s[42:43]
	v_cndmask_b32_e64 v153, v81, v153, s[42:43]
	v_cndmask_b32_e64 v156, v154, v155, s[44:45]
	v_cndmask_b32_e64 v157, v144, v153, s[44:45]
	s_nop 0
	v_mov_b32_dpp v156, v156 quad_perm:[1,0,3,2] row_mask:0xf bank_mask:0xf bound_ctrl:1
	v_mov_b32_dpp v157, v157 quad_perm:[1,0,3,2] row_mask:0xf bank_mask:0xf bound_ctrl:1
	v_cndmask_b32_e64 v154, v156, v154, s[44:45]
	v_cndmask_b32_e64 v155, v155, v156, s[44:45]
	v_cndmask_b32_e64 v156, v157, v144, s[44:45]
	v_cvt_pk_bf16_f32 v144, v146, v147
	v_cvt_pk_bf16_f32 v145, v152, v145
	v_cndmask_b32_e64 v153, v153, v157, s[44:45]
	v_cvt_pk_bf16_f32 v146, v154, v155
	v_cvt_pk_bf16_f32 v147, v156, v153
	global_store_dwordx4 v151, v[144:147], s[50:51] offset:64 sc1
	s_add_u32 s50, s0, s34
	s_addc_u32 s51, s55, s35
	v_cndmask_b32_e64 v144, v90, v92, s[42:43]
	v_cndmask_b32_e64 v145, v91, v93, s[42:43]
	s_add_u32 s0, s30, 0x20000
	v_mov_b32_dpp v144, v144 quad_perm:[2,3,0,1] row_mask:0xf bank_mask:0xf bound_ctrl:1
	v_mov_b32_dpp v145, v145 quad_perm:[2,3,0,1] row_mask:0xf bank_mask:0xf bound_ctrl:1
	v_cndmask_b32_e64 v146, v144, v90, s[42:43]
	v_cndmask_b32_e64 v147, v145, v91, s[42:43]
	v_cndmask_b32_e64 v144, v92, v144, s[42:43]
	v_cndmask_b32_e64 v145, v93, v145, s[42:43]
	v_cndmask_b32_e64 v152, v146, v147, s[44:45]
	v_cndmask_b32_e64 v153, v144, v145, s[44:45]
	s_addc_u32 s55, s31, 0
	v_mov_b32_dpp v152, v152 quad_perm:[1,0,3,2] row_mask:0xf bank_mask:0xf bound_ctrl:1
	v_mov_b32_dpp v153, v153 quad_perm:[1,0,3,2] row_mask:0xf bank_mask:0xf bound_ctrl:1
	v_cndmask_b32_e64 v146, v152, v146, s[44:45]
	v_cndmask_b32_e64 v147, v147, v152, s[44:45]
	v_cndmask_b32_e64 v152, v153, v144, s[44:45]
	v_cndmask_b32_e64 v145, v145, v153, s[44:45]
	v_cndmask_b32_e64 v144, v74, v76, s[42:43]
	v_cndmask_b32_e64 v153, v75, v77, s[42:43]
	s_nop 0
	v_mov_b32_dpp v144, v144 quad_perm:[2,3,0,1] row_mask:0xf bank_mask:0xf bound_ctrl:1
	v_mov_b32_dpp v153, v153 quad_perm:[2,3,0,1] row_mask:0xf bank_mask:0xf bound_ctrl:1
	v_cndmask_b32_e64 v154, v144, v74, s[42:43]
	v_cndmask_b32_e64 v155, v153, v75, s[42:43]
	v_cndmask_b32_e64 v144, v76, v144, s[42:43]
	v_cndmask_b32_e64 v153, v77, v153, s[42:43]
	v_cndmask_b32_e64 v156, v154, v155, s[44:45]
	v_cndmask_b32_e64 v157, v144, v153, s[44:45]
	s_nop 0
	v_mov_b32_dpp v156, v156 quad_perm:[1,0,3,2] row_mask:0xf bank_mask:0xf bound_ctrl:1
	v_mov_b32_dpp v157, v157 quad_perm:[1,0,3,2] row_mask:0xf bank_mask:0xf bound_ctrl:1
	v_cndmask_b32_e64 v154, v156, v154, s[44:45]
	v_cndmask_b32_e64 v155, v155, v156, s[44:45]
	v_cndmask_b32_e64 v156, v157, v144, s[44:45]
	v_cvt_pk_bf16_f32 v144, v146, v147
	v_cvt_pk_bf16_f32 v145, v152, v145
	v_cndmask_b32_e64 v153, v153, v157, s[44:45]
	v_cvt_pk_bf16_f32 v146, v154, v155
	v_cvt_pk_bf16_f32 v147, v156, v153
	global_store_dwordx4 v151, v[144:147], s[50:51] sc1
	s_nop 1
	v_cndmask_b32_e64 v144, v82, v84, s[42:43]
	v_cndmask_b32_e64 v145, v83, v85, s[42:43]
	s_nop 0
	v_mov_b32_dpp v144, v144 quad_perm:[2,3,0,1] row_mask:0xf bank_mask:0xf bound_ctrl:1
	v_mov_b32_dpp v145, v145 quad_perm:[2,3,0,1] row_mask:0xf bank_mask:0xf bound_ctrl:1
	v_cndmask_b32_e64 v146, v144, v82, s[42:43]
	v_cndmask_b32_e64 v147, v145, v83, s[42:43]
	v_cndmask_b32_e64 v144, v84, v144, s[42:43]
	v_cndmask_b32_e64 v145, v85, v145, s[42:43]
	v_cndmask_b32_e64 v152, v146, v147, s[44:45]
	v_cndmask_b32_e64 v153, v144, v145, s[44:45]
	s_nop 0
	v_mov_b32_dpp v152, v152 quad_perm:[1,0,3,2] row_mask:0xf bank_mask:0xf bound_ctrl:1
	v_mov_b32_dpp v153, v153 quad_perm:[1,0,3,2] row_mask:0xf bank_mask:0xf bound_ctrl:1
	v_cndmask_b32_e64 v146, v152, v146, s[44:45]
	v_cndmask_b32_e64 v147, v147, v152, s[44:45]
	v_cndmask_b32_e64 v152, v153, v144, s[44:45]
	v_cndmask_b32_e64 v145, v145, v153, s[44:45]
	v_cndmask_b32_e64 v144, v70, v72, s[42:43]
	v_cndmask_b32_e64 v153, v71, v73, s[42:43]
	s_nop 0
	v_mov_b32_dpp v144, v144 quad_perm:[2,3,0,1] row_mask:0xf bank_mask:0xf bound_ctrl:1
	v_mov_b32_dpp v153, v153 quad_perm:[2,3,0,1] row_mask:0xf bank_mask:0xf bound_ctrl:1
	v_cndmask_b32_e64 v154, v144, v70, s[42:43]
	v_cndmask_b32_e64 v155, v153, v71, s[42:43]
	v_cndmask_b32_e64 v144, v72, v144, s[42:43]
	v_cndmask_b32_e64 v153, v73, v153, s[42:43]
	v_cndmask_b32_e64 v156, v154, v155, s[44:45]
	v_cndmask_b32_e64 v157, v144, v153, s[44:45]
	s_nop 0
	v_mov_b32_dpp v156, v156 quad_perm:[1,0,3,2] row_mask:0xf bank_mask:0xf bound_ctrl:1
	v_mov_b32_dpp v157, v157 quad_perm:[1,0,3,2] row_mask:0xf bank_mask:0xf bound_ctrl:1
	v_cndmask_b32_e64 v154, v156, v154, s[44:45]
	v_cndmask_b32_e64 v155, v155, v156, s[44:45]
	v_cndmask_b32_e64 v156, v157, v144, s[44:45]
	v_cvt_pk_bf16_f32 v144, v146, v147
	v_cvt_pk_bf16_f32 v145, v152, v145
	v_cndmask_b32_e64 v153, v153, v157, s[44:45]
	v_cvt_pk_bf16_f32 v146, v154, v155
	v_cvt_pk_bf16_f32 v147, v156, v153
	global_store_dwordx4 v151, v[144:147], s[50:51] offset:64 sc1
	s_add_u32 s50, s0, s26
	s_addc_u32 s51, s55, s27
	v_cndmask_b32_e64 v144, v66, v68, s[42:43]
	v_cndmask_b32_e64 v145, v67, v69, s[42:43]
	s_nop 0
	v_mov_b32_dpp v144, v144 quad_perm:[2,3,0,1] row_mask:0xf bank_mask:0xf bound_ctrl:1
	v_mov_b32_dpp v145, v145 quad_perm:[2,3,0,1] row_mask:0xf bank_mask:0xf bound_ctrl:1
	v_cndmask_b32_e64 v146, v144, v66, s[42:43]
	v_cndmask_b32_e64 v147, v145, v67, s[42:43]
	v_cndmask_b32_e64 v144, v68, v144, s[42:43]
	v_cndmask_b32_e64 v145, v69, v145, s[42:43]
	v_cndmask_b32_e64 v152, v146, v147, s[44:45]
	v_cndmask_b32_e64 v153, v144, v145, s[44:45]
	s_nop 0
	v_mov_b32_dpp v152, v152 quad_perm:[1,0,3,2] row_mask:0xf bank_mask:0xf bound_ctrl:1
	v_mov_b32_dpp v153, v153 quad_perm:[1,0,3,2] row_mask:0xf bank_mask:0xf bound_ctrl:1
	v_cndmask_b32_e64 v146, v152, v146, s[44:45]
	v_cndmask_b32_e64 v147, v147, v152, s[44:45]
	v_cndmask_b32_e64 v152, v153, v144, s[44:45]
	v_cndmask_b32_e64 v145, v145, v153, s[44:45]
	v_cndmask_b32_e64 v144, v58, v60, s[42:43]
	v_cndmask_b32_e64 v153, v59, v61, s[42:43]
	s_nop 0
	v_mov_b32_dpp v144, v144 quad_perm:[2,3,0,1] row_mask:0xf bank_mask:0xf bound_ctrl:1
	v_mov_b32_dpp v153, v153 quad_perm:[2,3,0,1] row_mask:0xf bank_mask:0xf bound_ctrl:1
	v_cndmask_b32_e64 v154, v144, v58, s[42:43]
	v_cndmask_b32_e64 v155, v153, v59, s[42:43]
	v_cndmask_b32_e64 v144, v60, v144, s[42:43]
	v_cndmask_b32_e64 v153, v61, v153, s[42:43]
	v_cndmask_b32_e64 v156, v154, v155, s[44:45]
	v_cndmask_b32_e64 v157, v144, v153, s[44:45]
	s_nop 0
	v_mov_b32_dpp v156, v156 quad_perm:[1,0,3,2] row_mask:0xf bank_mask:0xf bound_ctrl:1
	v_mov_b32_dpp v157, v157 quad_perm:[1,0,3,2] row_mask:0xf bank_mask:0xf bound_ctrl:1
	v_cndmask_b32_e64 v154, v156, v154, s[44:45]
	v_cndmask_b32_e64 v155, v155, v156, s[44:45]
	v_cndmask_b32_e64 v156, v157, v144, s[44:45]
	v_cvt_pk_bf16_f32 v144, v146, v147
	v_cvt_pk_bf16_f32 v145, v152, v145
	v_cndmask_b32_e64 v153, v153, v157, s[44:45]
	v_cvt_pk_bf16_f32 v146, v154, v155
	v_cvt_pk_bf16_f32 v147, v156, v153
	global_store_dwordx4 v151, v[144:147], s[50:51] sc1
	s_nop 1
	v_cndmask_b32_e64 v144, v62, v64, s[42:43]
	v_cndmask_b32_e64 v145, v63, v65, s[42:43]
	s_nop 0
	v_mov_b32_dpp v144, v144 quad_perm:[2,3,0,1] row_mask:0xf bank_mask:0xf bound_ctrl:1
	v_mov_b32_dpp v145, v145 quad_perm:[2,3,0,1] row_mask:0xf bank_mask:0xf bound_ctrl:1
	v_cndmask_b32_e64 v146, v144, v62, s[42:43]
	v_cndmask_b32_e64 v147, v145, v63, s[42:43]
	v_cndmask_b32_e64 v144, v64, v144, s[42:43]
	v_cndmask_b32_e64 v145, v65, v145, s[42:43]
	v_cndmask_b32_e64 v152, v146, v147, s[44:45]
	v_cndmask_b32_e64 v153, v144, v145, s[44:45]
	s_nop 0
	v_mov_b32_dpp v152, v152 quad_perm:[1,0,3,2] row_mask:0xf bank_mask:0xf bound_ctrl:1
	v_mov_b32_dpp v153, v153 quad_perm:[1,0,3,2] row_mask:0xf bank_mask:0xf bound_ctrl:1
	v_cndmask_b32_e64 v146, v152, v146, s[44:45]
	v_cndmask_b32_e64 v147, v147, v152, s[44:45]
	v_cndmask_b32_e64 v152, v153, v144, s[44:45]
	v_cndmask_b32_e64 v145, v145, v153, s[44:45]
	v_cndmask_b32_e64 v144, v50, v52, s[42:43]
	v_cndmask_b32_e64 v153, v51, v53, s[42:43]
	s_nop 0
	v_mov_b32_dpp v144, v144 quad_perm:[2,3,0,1] row_mask:0xf bank_mask:0xf bound_ctrl:1
	v_mov_b32_dpp v153, v153 quad_perm:[2,3,0,1] row_mask:0xf bank_mask:0xf bound_ctrl:1
	v_cndmask_b32_e64 v154, v144, v50, s[42:43]
	v_cndmask_b32_e64 v155, v153, v51, s[42:43]
	v_cndmask_b32_e64 v144, v52, v144, s[42:43]
	v_cndmask_b32_e64 v153, v53, v153, s[42:43]
	v_cndmask_b32_e64 v156, v154, v155, s[44:45]
	v_cndmask_b32_e64 v157, v144, v153, s[44:45]
	s_nop 0
	v_mov_b32_dpp v156, v156 quad_perm:[1,0,3,2] row_mask:0xf bank_mask:0xf bound_ctrl:1
	v_mov_b32_dpp v157, v157 quad_perm:[1,0,3,2] row_mask:0xf bank_mask:0xf bound_ctrl:1
	v_cndmask_b32_e64 v154, v156, v154, s[44:45]
	v_cndmask_b32_e64 v155, v155, v156, s[44:45]
	v_cndmask_b32_e64 v156, v157, v144, s[44:45]
	v_cvt_pk_bf16_f32 v144, v146, v147
	v_cvt_pk_bf16_f32 v145, v152, v145
	v_cndmask_b32_e64 v153, v153, v157, s[44:45]
	v_cvt_pk_bf16_f32 v146, v154, v155
	v_cvt_pk_bf16_f32 v147, v156, v153
	global_store_dwordx4 v151, v[144:147], s[50:51] offset:64 sc1
	s_add_u32 s50, s0, s34
	s_addc_u32 s51, s55, s35
	v_cndmask_b32_e64 v144, v54, v56, s[42:43]
	v_cndmask_b32_e64 v145, v55, v57, s[42:43]
	s_add_u32 s0, s30, 0x28000
	v_mov_b32_dpp v144, v144 quad_perm:[2,3,0,1] row_mask:0xf bank_mask:0xf bound_ctrl:1
	v_mov_b32_dpp v145, v145 quad_perm:[2,3,0,1] row_mask:0xf bank_mask:0xf bound_ctrl:1
	v_cndmask_b32_e64 v146, v144, v54, s[42:43]
	v_cndmask_b32_e64 v147, v145, v55, s[42:43]
	v_cndmask_b32_e64 v144, v56, v144, s[42:43]
	v_cndmask_b32_e64 v145, v57, v145, s[42:43]
	v_cndmask_b32_e64 v152, v146, v147, s[44:45]
	v_cndmask_b32_e64 v153, v144, v145, s[44:45]
	s_addc_u32 s30, s31, 0
	v_mov_b32_dpp v152, v152 quad_perm:[1,0,3,2] row_mask:0xf bank_mask:0xf bound_ctrl:1
	v_mov_b32_dpp v153, v153 quad_perm:[1,0,3,2] row_mask:0xf bank_mask:0xf bound_ctrl:1
	v_cndmask_b32_e64 v146, v152, v146, s[44:45]
	v_cndmask_b32_e64 v147, v147, v152, s[44:45]
	v_cndmask_b32_e64 v152, v153, v144, s[44:45]
	v_cndmask_b32_e64 v145, v145, v153, s[44:45]
	v_cndmask_b32_e64 v144, v38, v40, s[42:43]
	v_cndmask_b32_e64 v153, v39, v41, s[42:43]
	s_add_u32 s26, s0, s26
	v_mov_b32_dpp v144, v144 quad_perm:[2,3,0,1] row_mask:0xf bank_mask:0xf bound_ctrl:1
	v_mov_b32_dpp v153, v153 quad_perm:[2,3,0,1] row_mask:0xf bank_mask:0xf bound_ctrl:1
	v_cndmask_b32_e64 v154, v144, v38, s[42:43]
	v_cndmask_b32_e64 v155, v153, v39, s[42:43]
	v_cndmask_b32_e64 v144, v40, v144, s[42:43]
	v_cndmask_b32_e64 v153, v41, v153, s[42:43]
	v_cndmask_b32_e64 v156, v154, v155, s[44:45]
	v_cndmask_b32_e64 v157, v144, v153, s[44:45]
	s_addc_u32 s27, s30, s27
	v_mov_b32_dpp v156, v156 quad_perm:[1,0,3,2] row_mask:0xf bank_mask:0xf bound_ctrl:1
	v_mov_b32_dpp v157, v157 quad_perm:[1,0,3,2] row_mask:0xf bank_mask:0xf bound_ctrl:1
	v_cndmask_b32_e64 v154, v156, v154, s[44:45]
	v_cndmask_b32_e64 v155, v155, v156, s[44:45]
	v_cndmask_b32_e64 v156, v157, v144, s[44:45]
	v_cvt_pk_bf16_f32 v144, v146, v147
	v_cvt_pk_bf16_f32 v145, v152, v145
	v_cndmask_b32_e64 v153, v153, v157, s[44:45]
	v_cvt_pk_bf16_f32 v146, v154, v155
	v_cvt_pk_bf16_f32 v147, v156, v153
	global_store_dwordx4 v151, v[144:147], s[50:51] sc1
	s_nop 1
	v_cndmask_b32_e64 v144, v46, v48, s[42:43]
	v_cndmask_b32_e64 v145, v47, v49, s[42:43]
	s_nop 0
	v_mov_b32_dpp v144, v144 quad_perm:[2,3,0,1] row_mask:0xf bank_mask:0xf bound_ctrl:1
	v_mov_b32_dpp v145, v145 quad_perm:[2,3,0,1] row_mask:0xf bank_mask:0xf bound_ctrl:1
	v_cndmask_b32_e64 v146, v144, v46, s[42:43]
	v_cndmask_b32_e64 v147, v145, v47, s[42:43]
	v_cndmask_b32_e64 v144, v48, v144, s[42:43]
	v_cndmask_b32_e64 v145, v49, v145, s[42:43]
	v_cndmask_b32_e64 v152, v146, v147, s[44:45]
	v_cndmask_b32_e64 v153, v144, v145, s[44:45]
	s_nop 0
	v_mov_b32_dpp v152, v152 quad_perm:[1,0,3,2] row_mask:0xf bank_mask:0xf bound_ctrl:1
	v_mov_b32_dpp v153, v153 quad_perm:[1,0,3,2] row_mask:0xf bank_mask:0xf bound_ctrl:1
	v_cndmask_b32_e64 v146, v152, v146, s[44:45]
	v_cndmask_b32_e64 v147, v147, v152, s[44:45]
	v_cndmask_b32_e64 v152, v153, v144, s[44:45]
	v_cndmask_b32_e64 v145, v145, v153, s[44:45]
	v_cndmask_b32_e64 v144, v24, v26, s[42:43]
	v_cndmask_b32_e64 v153, v25, v27, s[42:43]
	s_nop 0
	v_mov_b32_dpp v144, v144 quad_perm:[2,3,0,1] row_mask:0xf bank_mask:0xf bound_ctrl:1
	v_mov_b32_dpp v153, v153 quad_perm:[2,3,0,1] row_mask:0xf bank_mask:0xf bound_ctrl:1
	v_cndmask_b32_e64 v154, v144, v24, s[42:43]
	v_cndmask_b32_e64 v155, v153, v25, s[42:43]
	v_cndmask_b32_e64 v144, v26, v144, s[42:43]
	v_cndmask_b32_e64 v153, v27, v153, s[42:43]
	v_cndmask_b32_e64 v156, v154, v155, s[44:45]
	v_cndmask_b32_e64 v157, v144, v153, s[44:45]
	s_nop 0
	v_mov_b32_dpp v156, v156 quad_perm:[1,0,3,2] row_mask:0xf bank_mask:0xf bound_ctrl:1
	v_mov_b32_dpp v157, v157 quad_perm:[1,0,3,2] row_mask:0xf bank_mask:0xf bound_ctrl:1
	v_cndmask_b32_e64 v154, v156, v154, s[44:45]
	v_cndmask_b32_e64 v155, v155, v156, s[44:45]
	v_cndmask_b32_e64 v156, v157, v144, s[44:45]
	v_cvt_pk_bf16_f32 v144, v146, v147
	v_cvt_pk_bf16_f32 v145, v152, v145
	v_cndmask_b32_e64 v153, v153, v157, s[44:45]
	v_cvt_pk_bf16_f32 v146, v154, v155
	v_cvt_pk_bf16_f32 v147, v156, v153
	global_store_dwordx4 v151, v[144:147], s[50:51] offset:64 sc1
	s_nop 1
	v_cndmask_b32_e64 v144, v42, v44, s[42:43]
	v_cndmask_b32_e64 v145, v43, v45, s[42:43]
	s_nop 0
	v_mov_b32_dpp v144, v144 quad_perm:[2,3,0,1] row_mask:0xf bank_mask:0xf bound_ctrl:1
	v_mov_b32_dpp v145, v145 quad_perm:[2,3,0,1] row_mask:0xf bank_mask:0xf bound_ctrl:1
	v_cndmask_b32_e64 v146, v144, v42, s[42:43]
	v_cndmask_b32_e64 v147, v145, v43, s[42:43]
	v_cndmask_b32_e64 v144, v44, v144, s[42:43]
	v_cndmask_b32_e64 v145, v45, v145, s[42:43]
	v_cndmask_b32_e64 v152, v146, v147, s[44:45]
	v_cndmask_b32_e64 v153, v144, v145, s[44:45]
	s_nop 0
	v_mov_b32_dpp v152, v152 quad_perm:[1,0,3,2] row_mask:0xf bank_mask:0xf bound_ctrl:1
	v_mov_b32_dpp v153, v153 quad_perm:[1,0,3,2] row_mask:0xf bank_mask:0xf bound_ctrl:1
	v_cndmask_b32_e64 v146, v152, v146, s[44:45]
	v_cndmask_b32_e64 v147, v147, v152, s[44:45]
	v_cndmask_b32_e64 v152, v153, v144, s[44:45]
	v_cndmask_b32_e64 v145, v145, v153, s[44:45]
	v_cndmask_b32_e64 v144, v20, v22, s[42:43]
	v_cndmask_b32_e64 v153, v21, v23, s[42:43]
	s_nop 0
	v_mov_b32_dpp v144, v144 quad_perm:[2,3,0,1] row_mask:0xf bank_mask:0xf bound_ctrl:1
	v_mov_b32_dpp v153, v153 quad_perm:[2,3,0,1] row_mask:0xf bank_mask:0xf bound_ctrl:1
	v_cndmask_b32_e64 v154, v144, v20, s[42:43]
	v_cndmask_b32_e64 v155, v153, v21, s[42:43]
	v_cndmask_b32_e64 v144, v22, v144, s[42:43]
	v_cndmask_b32_e64 v153, v23, v153, s[42:43]
	v_cndmask_b32_e64 v156, v154, v155, s[44:45]
	v_cndmask_b32_e64 v157, v144, v153, s[44:45]
	s_nop 0
	v_mov_b32_dpp v156, v156 quad_perm:[1,0,3,2] row_mask:0xf bank_mask:0xf bound_ctrl:1
	v_mov_b32_dpp v157, v157 quad_perm:[1,0,3,2] row_mask:0xf bank_mask:0xf bound_ctrl:1
	v_cndmask_b32_e64 v154, v156, v154, s[44:45]
	v_cndmask_b32_e64 v155, v155, v156, s[44:45]
	v_cndmask_b32_e64 v156, v157, v144, s[44:45]
	v_cvt_pk_bf16_f32 v144, v146, v147
	v_cvt_pk_bf16_f32 v145, v152, v145
	v_cndmask_b32_e64 v153, v153, v157, s[44:45]
	v_cvt_pk_bf16_f32 v146, v154, v155
	v_cvt_pk_bf16_f32 v147, v156, v153
	global_store_dwordx4 v151, v[144:147], s[26:27] sc1
	s_nop 1
	v_cndmask_b32_e64 v144, v28, v30, s[42:43]
	v_cndmask_b32_e64 v145, v29, v31, s[42:43]
	s_nop 0
	v_mov_b32_dpp v144, v144 quad_perm:[2,3,0,1] row_mask:0xf bank_mask:0xf bound_ctrl:1
	v_mov_b32_dpp v145, v145 quad_perm:[2,3,0,1] row_mask:0xf bank_mask:0xf bound_ctrl:1
	v_cndmask_b32_e64 v146, v144, v28, s[42:43]
	v_cndmask_b32_e64 v147, v145, v29, s[42:43]
	v_cndmask_b32_e64 v144, v30, v144, s[42:43]
	v_cndmask_b32_e64 v145, v31, v145, s[42:43]
	v_cndmask_b32_e64 v152, v146, v147, s[44:45]
	v_cndmask_b32_e64 v153, v144, v145, s[44:45]
	s_nop 0
	v_mov_b32_dpp v152, v152 quad_perm:[1,0,3,2] row_mask:0xf bank_mask:0xf bound_ctrl:1
	v_mov_b32_dpp v153, v153 quad_perm:[1,0,3,2] row_mask:0xf bank_mask:0xf bound_ctrl:1
	v_cndmask_b32_e64 v146, v152, v146, s[44:45]
	v_cndmask_b32_e64 v147, v147, v152, s[44:45]
	v_cndmask_b32_e64 v152, v153, v144, s[44:45]
	v_cndmask_b32_e64 v145, v145, v153, s[44:45]
	v_cndmask_b32_e64 v144, v12, v14, s[42:43]
	v_cndmask_b32_e64 v153, v13, v15, s[42:43]
	s_nop 0
	v_mov_b32_dpp v144, v144 quad_perm:[2,3,0,1] row_mask:0xf bank_mask:0xf bound_ctrl:1
	v_mov_b32_dpp v153, v153 quad_perm:[2,3,0,1] row_mask:0xf bank_mask:0xf bound_ctrl:1
	v_cndmask_b32_e64 v154, v144, v12, s[42:43]
	v_cndmask_b32_e64 v155, v153, v13, s[42:43]
	v_cndmask_b32_e64 v144, v14, v144, s[42:43]
	v_cndmask_b32_e64 v153, v15, v153, s[42:43]
	v_cndmask_b32_e64 v156, v154, v155, s[44:45]
	v_cndmask_b32_e64 v157, v144, v153, s[44:45]
	s_nop 0
	v_mov_b32_dpp v156, v156 quad_perm:[1,0,3,2] row_mask:0xf bank_mask:0xf bound_ctrl:1
	v_mov_b32_dpp v157, v157 quad_perm:[1,0,3,2] row_mask:0xf bank_mask:0xf bound_ctrl:1
	v_cndmask_b32_e64 v154, v156, v154, s[44:45]
	v_cndmask_b32_e64 v155, v155, v156, s[44:45]
	v_cndmask_b32_e64 v156, v157, v144, s[44:45]
	v_cvt_pk_bf16_f32 v144, v146, v147
	v_cvt_pk_bf16_f32 v145, v152, v145
	v_cndmask_b32_e64 v153, v153, v157, s[44:45]
	v_cvt_pk_bf16_f32 v146, v154, v155
	v_cvt_pk_bf16_f32 v147, v156, v153
	global_store_dwordx4 v151, v[144:147], s[26:27] offset:64 sc1
	s_add_u32 s26, s0, s34
	s_addc_u32 s27, s30, s35
	v_cndmask_b32_e64 v144, v16, v18, s[42:43]
	v_cndmask_b32_e64 v145, v17, v19, s[42:43]
	s_nop 0
	v_mov_b32_dpp v144, v144 quad_perm:[2,3,0,1] row_mask:0xf bank_mask:0xf bound_ctrl:1
	v_mov_b32_dpp v145, v145 quad_perm:[2,3,0,1] row_mask:0xf bank_mask:0xf bound_ctrl:1
	v_cndmask_b32_e64 v146, v144, v16, s[42:43]
	v_cndmask_b32_e64 v147, v145, v17, s[42:43]
	v_cndmask_b32_e64 v144, v18, v144, s[42:43]
	v_cndmask_b32_e64 v145, v19, v145, s[42:43]
	v_cndmask_b32_e64 v152, v146, v147, s[44:45]
	v_cndmask_b32_e64 v153, v144, v145, s[44:45]
	s_nop 0
	v_mov_b32_dpp v152, v152 quad_perm:[1,0,3,2] row_mask:0xf bank_mask:0xf bound_ctrl:1
	v_mov_b32_dpp v153, v153 quad_perm:[1,0,3,2] row_mask:0xf bank_mask:0xf bound_ctrl:1
	v_cndmask_b32_e64 v146, v152, v146, s[44:45]
	v_cndmask_b32_e64 v147, v147, v152, s[44:45]
	v_cndmask_b32_e64 v152, v153, v144, s[44:45]
	v_cndmask_b32_e64 v145, v145, v153, s[44:45]
	v_cndmask_b32_e64 v144, v4, v6, s[42:43]
	v_cndmask_b32_e64 v153, v5, v7, s[42:43]
	s_nop 0
	v_mov_b32_dpp v144, v144 quad_perm:[2,3,0,1] row_mask:0xf bank_mask:0xf bound_ctrl:1
	v_mov_b32_dpp v153, v153 quad_perm:[2,3,0,1] row_mask:0xf bank_mask:0xf bound_ctrl:1
	v_cndmask_b32_e64 v154, v144, v4, s[42:43]
	v_cndmask_b32_e64 v155, v153, v5, s[42:43]
	v_cndmask_b32_e64 v144, v6, v144, s[42:43]
	v_cndmask_b32_e64 v153, v7, v153, s[42:43]
	v_cndmask_b32_e64 v156, v154, v155, s[44:45]
	v_cndmask_b32_e64 v157, v144, v153, s[44:45]
	s_nop 0
	v_mov_b32_dpp v156, v156 quad_perm:[1,0,3,2] row_mask:0xf bank_mask:0xf bound_ctrl:1
	v_mov_b32_dpp v157, v157 quad_perm:[1,0,3,2] row_mask:0xf bank_mask:0xf bound_ctrl:1
	v_cndmask_b32_e64 v154, v156, v154, s[44:45]
	v_cndmask_b32_e64 v155, v155, v156, s[44:45]
	v_cndmask_b32_e64 v156, v157, v144, s[44:45]
	v_cvt_pk_bf16_f32 v144, v146, v147
	v_cvt_pk_bf16_f32 v145, v152, v145
	v_cndmask_b32_e64 v153, v153, v157, s[44:45]
	v_cvt_pk_bf16_f32 v146, v154, v155
	v_cvt_pk_bf16_f32 v147, v156, v153
	global_store_dwordx4 v151, v[144:147], s[26:27] sc1
	s_nop 1
	v_cndmask_b32_e64 v144, v8, v10, s[42:43]
	v_cndmask_b32_e64 v145, v9, v11, s[42:43]
	s_nop 0
	v_mov_b32_dpp v144, v144 quad_perm:[2,3,0,1] row_mask:0xf bank_mask:0xf bound_ctrl:1
	v_mov_b32_dpp v145, v145 quad_perm:[2,3,0,1] row_mask:0xf bank_mask:0xf bound_ctrl:1
	v_cndmask_b32_e64 v146, v144, v8, s[42:43]
	v_cndmask_b32_e64 v147, v145, v9, s[42:43]
	v_cndmask_b32_e64 v144, v10, v144, s[42:43]
	v_cndmask_b32_e64 v145, v11, v145, s[42:43]
	v_cndmask_b32_e64 v152, v146, v147, s[44:45]
	v_cndmask_b32_e64 v153, v144, v145, s[44:45]
	s_nop 0
	v_mov_b32_dpp v152, v152 quad_perm:[1,0,3,2] row_mask:0xf bank_mask:0xf bound_ctrl:1
	v_mov_b32_dpp v153, v153 quad_perm:[1,0,3,2] row_mask:0xf bank_mask:0xf bound_ctrl:1
	v_cndmask_b32_e64 v146, v152, v146, s[44:45]
	v_cndmask_b32_e64 v147, v147, v152, s[44:45]
	v_cndmask_b32_e64 v152, v153, v144, s[44:45]
	v_cndmask_b32_e64 v145, v145, v153, s[44:45]
	v_cndmask_b32_e64 v144, v0, v2, s[42:43]
	v_cndmask_b32_e64 v153, v1, v3, s[42:43]
	s_nop 0
	v_mov_b32_dpp v144, v144 quad_perm:[2,3,0,1] row_mask:0xf bank_mask:0xf bound_ctrl:1
	v_mov_b32_dpp v153, v153 quad_perm:[2,3,0,1] row_mask:0xf bank_mask:0xf bound_ctrl:1
	v_cndmask_b32_e64 v154, v144, v0, s[42:43]
	v_cndmask_b32_e64 v155, v153, v1, s[42:43]
	v_cndmask_b32_e64 v144, v2, v144, s[42:43]
	v_cndmask_b32_e64 v153, v3, v153, s[42:43]
	v_cndmask_b32_e64 v156, v154, v155, s[44:45]
	v_cndmask_b32_e64 v157, v144, v153, s[44:45]
	s_nop 0
	v_mov_b32_dpp v156, v156 quad_perm:[1,0,3,2] row_mask:0xf bank_mask:0xf bound_ctrl:1
	v_mov_b32_dpp v157, v157 quad_perm:[1,0,3,2] row_mask:0xf bank_mask:0xf bound_ctrl:1
	v_cndmask_b32_e64 v154, v156, v154, s[44:45]
	v_cndmask_b32_e64 v155, v155, v156, s[44:45]
	v_cndmask_b32_e64 v156, v157, v144, s[44:45]
	v_cndmask_b32_e64 v153, v153, v157, s[44:45]
	v_cvt_pk_bf16_f32 v144, v146, v147
	v_cvt_pk_bf16_f32 v145, v152, v145
	v_cvt_pk_bf16_f32 v146, v154, v155
	v_cvt_pk_bf16_f32 v147, v156, v153
	global_store_dwordx4 v151, v[144:147], s[26:27] offset:64 sc1
	s_mov_b64 s[26:27], 0
.LBB0_192:
	s_andn2_b64 vcc, exec, s[26:27]
	s_cbranch_vccnz .LBB0_194
	s_cmp_lt_u32 s62, 6
	s_cselect_b64 vcc, -1, 0
	s_and_b64 s[26:27], vcc, exec
	v_readlane_b32 s0, v252, 10
	v_readlane_b32 s26, v252, 50
	s_cselect_b32 s31, s0, s26
	v_readlane_b32 s0, v252, 9
	v_readlane_b32 s26, v252, 48
	s_cselect_b32 s30, s0, s26
	s_lshl_b32 s0, s64, 8
	s_add_i32 s0, s0, s38
	s_ashr_i32 s26, s0, 4
	s_lshl_b32 s0, s62, 2
	v_mov_b32_e32 v144, 0x3e38aa3b
	v_lshl_add_u64 v[156:157], s[30:31], 0, v[32:33]
	s_ashr_i32 s27, s26, 31
	s_and_b32 s0, s0, 4
	v_readlane_b32 s30, v255, 15
	v_cndmask_b32_e32 v144, 1.0, v144, vcc
	s_or_b32 s0, s0, s30
	s_lshl_b64 s[30:31], s[26:27], 14
	v_lshl_add_u64 v[146:147], v[156:157], 0, s[30:31]
	s_lshl_b32 s0, s0, 11
	v_pk_mul_f32 v[154:155], v[144:145], v[132:133] op_sel_hi:[0,1]
	v_pk_mul_f32 v[152:153], v[144:145], v[130:131] op_sel_hi:[0,1]
	v_lshl_add_u64 v[146:147], v[146:147], 0, s[0:1]
	v_pk_mul_f32 v[158:159], v[144:145], v[128:129] op_sel_hi:[0,1]
	v_pk_mul_f32 v[160:161], v[144:145], v[126:127] op_sel_hi:[0,1]
	v_cvt_pk_bf16_f32 v152, v152, v153
	v_cvt_pk_bf16_f32 v153, v154, v155
	v_cvt_pk_bf16_f32 v154, v160, v161
	v_cvt_pk_bf16_f32 v155, v158, v159
	global_store_dwordx4 v[146:147], v[152:155], off sc1
	v_pk_mul_f32 v[158:159], v[144:145], v[112:113] op_sel_hi:[0,1]
	s_movk_i32 s34, 0x1000
	v_pk_mul_f32 v[154:155], v[144:145], v[120:121] op_sel_hi:[0,1]
	v_pk_mul_f32 v[152:153], v[144:145], v[118:119] op_sel_hi:[0,1]
	s_or_b32 s30, s26, 1
	v_pk_mul_f32 v[160:161], v[144:145], v[110:111] op_sel_hi:[0,1]
	v_cvt_pk_bf16_f32 v152, v152, v153
	v_cvt_pk_bf16_f32 v153, v154, v155
	v_cvt_pk_bf16_f32 v154, v160, v161
	v_cvt_pk_bf16_f32 v155, v158, v159
	v_add_co_u32_e32 v158, vcc, s34, v146
	s_ashr_i32 s31, s30, 31
	s_nop 0
	v_addc_co_u32_e32 v159, vcc, 0, v147, vcc
	s_lshl_b64 s[30:31], s[30:31], 14
	global_store_dwordx4 v[158:159], v[152:155], off sc1
	v_pk_mul_f32 v[160:161], v[144:145], v[116:117] op_sel_hi:[0,1]
	v_pk_mul_f32 v[162:163], v[144:145], v[114:115] op_sel_hi:[0,1]
	v_lshl_add_u64 v[152:153], v[156:157], 0, s[30:31]
	v_lshl_add_u64 v[158:159], v[152:153], 0, s[0:1]
	v_pk_mul_f32 v[152:153], v[144:145], v[122:123] op_sel_hi:[0,1]
	v_pk_mul_f32 v[154:155], v[144:145], v[124:125] op_sel_hi:[0,1]
	v_cvt_pk_bf16_f32 v152, v152, v153
	v_cvt_pk_bf16_f32 v153, v154, v155
	s_or_b32 s30, s26, 2
	v_cvt_pk_bf16_f32 v154, v162, v163
	v_cvt_pk_bf16_f32 v155, v160, v161
	global_store_dwordx4 v[158:159], v[152:155], off sc1
	v_add_co_u32_e32 v158, vcc, s34, v158
	s_nop 0
	v_pk_mul_f32 v[152:153], v[144:145], v[102:103] op_sel_hi:[0,1]
	s_ashr_i32 s31, s30, 31
	v_pk_mul_f32 v[154:155], v[144:145], v[104:105] op_sel_hi:[0,1]
	v_cvt_pk_bf16_f32 v152, v152, v153
	v_cvt_pk_bf16_f32 v153, v154, v155
	v_addc_co_u32_e32 v159, vcc, 0, v159, vcc
	s_lshl_b64 s[30:31], s[30:31], 14
	v_pk_mul_f32 v[160:161], v[144:145], v[96:97] op_sel_hi:[0,1]
	v_pk_mul_f32 v[162:163], v[144:145], v[94:95] op_sel_hi:[0,1]
	v_cvt_pk_bf16_f32 v154, v162, v163
	v_cvt_pk_bf16_f32 v155, v160, v161
	global_store_dwordx4 v[158:159], v[152:155], off sc1
	s_or_b32 s26, s26, 3
	v_pk_mul_f32 v[160:161], v[144:145], v[100:101] op_sel_hi:[0,1]
	v_lshl_add_u64 v[152:153], v[156:157], 0, s[30:31]
	v_lshl_add_u64 v[158:159], v[152:153], 0, s[0:1]
	v_pk_mul_f32 v[152:153], v[144:145], v[106:107] op_sel_hi:[0,1]
	v_pk_mul_f32 v[154:155], v[144:145], v[108:109] op_sel_hi:[0,1]
	v_cvt_pk_bf16_f32 v152, v152, v153
	v_cvt_pk_bf16_f32 v153, v154, v155
	v_pk_mul_f32 v[162:163], v[144:145], v[98:99] op_sel_hi:[0,1]
	v_cvt_pk_bf16_f32 v154, v162, v163
	v_cvt_pk_bf16_f32 v155, v160, v161
	global_store_dwordx4 v[158:159], v[152:155], off sc1
	v_add_co_u32_e32 v158, vcc, s34, v158
	s_nop 0
	v_pk_mul_f32 v[152:153], v[144:145], v[90:91] op_sel_hi:[0,1]
	s_ashr_i32 s27, s26, 31
	v_pk_mul_f32 v[154:155], v[144:145], v[92:93] op_sel_hi:[0,1]
	v_cvt_pk_bf16_f32 v152, v152, v153
	v_cvt_pk_bf16_f32 v153, v154, v155
	v_addc_co_u32_e32 v159, vcc, 0, v159, vcc
	s_lshl_b64 s[26:27], s[26:27], 14
	v_pk_mul_f32 v[160:161], v[144:145], v[84:85] op_sel_hi:[0,1]
	v_pk_mul_f32 v[162:163], v[144:145], v[82:83] op_sel_hi:[0,1]
	v_cvt_pk_bf16_f32 v154, v162, v163
	v_cvt_pk_bf16_f32 v155, v160, v161
	global_store_dwordx4 v[158:159], v[152:155], off sc1
	v_pk_mul_f32 v[158:159], v[144:145], v[80:81] op_sel_hi:[0,1]
	v_pk_mul_f32 v[160:161], v[144:145], v[78:79] op_sel_hi:[0,1]
	v_lshl_add_u64 v[152:153], v[156:157], 0, s[26:27]
	v_lshl_add_u64 v[156:157], v[152:153], 0, s[0:1]
	v_pk_mul_f32 v[154:155], v[144:145], v[88:89] op_sel_hi:[0,1]
	v_pk_mul_f32 v[152:153], v[144:145], v[86:87] op_sel_hi:[0,1]
	v_cvt_pk_bf16_f32 v152, v152, v153
	v_cvt_pk_bf16_f32 v153, v154, v155
	v_cvt_pk_bf16_f32 v154, v160, v161
	v_cvt_pk_bf16_f32 v155, v158, v159
	global_store_dwordx4 v[156:157], v[152:155], off sc1
	v_add_co_u32_e32 v156, vcc, s34, v156
	s_nop 0
	v_pk_mul_f32 v[154:155], v[144:145], v[76:77] op_sel_hi:[0,1]
	v_pk_mul_f32 v[152:153], v[144:145], v[74:75] op_sel_hi:[0,1]
	v_pk_mul_f32 v[158:159], v[144:145], v[72:73] op_sel_hi:[0,1]
	v_pk_mul_f32 v[160:161], v[144:145], v[70:71] op_sel_hi:[0,1]
	v_cvt_pk_bf16_f32 v152, v152, v153
	v_cvt_pk_bf16_f32 v153, v154, v155
	v_cvt_pk_bf16_f32 v154, v160, v161
	v_cvt_pk_bf16_f32 v155, v158, v159
	v_addc_co_u32_e32 v157, vcc, 0, v157, vcc
	global_store_dwordx4 v[156:157], v[152:155], off sc1
	v_pk_mul_f32 v[156:157], v[144:145], v[64:65] op_sel_hi:[0,1]
	s_mov_b32 s0, 0x21000
	v_pk_mul_f32 v[154:155], v[144:145], v[68:69] op_sel_hi:[0,1]
	v_pk_mul_f32 v[152:153], v[144:145], v[66:67] op_sel_hi:[0,1]
	v_pk_mul_f32 v[158:159], v[144:145], v[62:63] op_sel_hi:[0,1]
	v_cvt_pk_bf16_f32 v152, v152, v153
	v_cvt_pk_bf16_f32 v153, v154, v155
	v_cvt_pk_bf16_f32 v154, v158, v159
	v_cvt_pk_bf16_f32 v155, v156, v157
	v_add_co_u32_e32 v156, vcc, s0, v146
	v_pk_mul_f32 v[158:159], v[144:145], v[48:49] op_sel_hi:[0,1]
	s_nop 0
	v_addc_co_u32_e32 v157, vcc, 0, v147, vcc
	global_store_dwordx4 v[156:157], v[152:155], off offset:-4096 sc1
	v_pk_mul_f32 v[160:161], v[144:145], v[46:47] op_sel_hi:[0,1]
	s_mov_b32 s0, 0x25000
	v_pk_mul_f32 v[154:155], v[144:145], v[56:57] op_sel_hi:[0,1]
	v_pk_mul_f32 v[152:153], v[144:145], v[54:55] op_sel_hi:[0,1]
	v_cvt_pk_bf16_f32 v152, v152, v153
	v_cvt_pk_bf16_f32 v153, v154, v155
	v_cvt_pk_bf16_f32 v154, v160, v161
	v_cvt_pk_bf16_f32 v155, v158, v159
	global_store_dwordx4 v[156:157], v[152:155], off sc1
	v_pk_mul_f32 v[156:157], v[144:145], v[52:53] op_sel_hi:[0,1]
	v_pk_mul_f32 v[158:159], v[144:145], v[50:51] op_sel_hi:[0,1]
	v_pk_mul_f32 v[154:155], v[144:145], v[60:61] op_sel_hi:[0,1]
	v_pk_mul_f32 v[152:153], v[144:145], v[58:59] op_sel_hi:[0,1]
	v_cvt_pk_bf16_f32 v152, v152, v153
	v_cvt_pk_bf16_f32 v153, v154, v155
	v_cvt_pk_bf16_f32 v154, v158, v159
	v_cvt_pk_bf16_f32 v155, v156, v157
	v_add_co_u32_e32 v156, vcc, s0, v146
	v_pk_mul_f32 v[158:159], v[144:145], v[26:27] op_sel_hi:[0,1]
	s_nop 0
	v_addc_co_u32_e32 v157, vcc, 0, v147, vcc
	global_store_dwordx4 v[156:157], v[152:155], off offset:-4096 sc1
	v_pk_mul_f32 v[160:161], v[144:145], v[24:25] op_sel_hi:[0,1]
	s_mov_b32 s0, 0x29000
	v_pk_mul_f32 v[154:155], v[144:145], v[40:41] op_sel_hi:[0,1]
	v_pk_mul_f32 v[152:153], v[144:145], v[38:39] op_sel_hi:[0,1]
	v_cvt_pk_bf16_f32 v152, v152, v153
	v_cvt_pk_bf16_f32 v153, v154, v155
	v_cvt_pk_bf16_f32 v154, v160, v161
	v_cvt_pk_bf16_f32 v155, v158, v159
	global_store_dwordx4 v[156:157], v[152:155], off sc1
	v_pk_mul_f32 v[156:157], v[144:145], v[30:31] op_sel_hi:[0,1]
	v_pk_mul_f32 v[158:159], v[144:145], v[28:29] op_sel_hi:[0,1]
	v_pk_mul_f32 v[154:155], v[144:145], v[44:45] op_sel_hi:[0,1]
	v_pk_mul_f32 v[152:153], v[144:145], v[42:43] op_sel_hi:[0,1]
	v_cvt_pk_bf16_f32 v152, v152, v153
	v_cvt_pk_bf16_f32 v153, v154, v155
	v_cvt_pk_bf16_f32 v154, v158, v159
	v_cvt_pk_bf16_f32 v155, v156, v157
	v_add_co_u32_e32 v156, vcc, s0, v146
	v_pk_mul_f32 v[158:159], v[144:145], v[10:11] op_sel_hi:[0,1]
	s_nop 0
	v_addc_co_u32_e32 v157, vcc, 0, v147, vcc
	global_store_dwordx4 v[156:157], v[152:155], off offset:-4096 sc1
	v_pk_mul_f32 v[160:161], v[144:145], v[8:9] op_sel_hi:[0,1]
	s_mov_b32 s0, 0x2c000
	v_pk_mul_f32 v[154:155], v[144:145], v[18:19] op_sel_hi:[0,1]
	v_pk_mul_f32 v[152:153], v[144:145], v[16:17] op_sel_hi:[0,1]
	v_cvt_pk_bf16_f32 v152, v152, v153
	v_cvt_pk_bf16_f32 v153, v154, v155
	v_cvt_pk_bf16_f32 v154, v160, v161
	v_cvt_pk_bf16_f32 v155, v158, v159
	global_store_dwordx4 v[156:157], v[152:155], off sc1
	v_pk_mul_f32 v[156:157], v[144:145], v[14:15] op_sel_hi:[0,1]
	v_pk_mul_f32 v[158:159], v[144:145], v[12:13] op_sel_hi:[0,1]
	v_pk_mul_f32 v[154:155], v[144:145], v[22:23] op_sel_hi:[0,1]
	v_pk_mul_f32 v[152:153], v[144:145], v[20:21] op_sel_hi:[0,1]
	v_cvt_pk_bf16_f32 v152, v152, v153
	v_cvt_pk_bf16_f32 v153, v154, v155
	v_cvt_pk_bf16_f32 v154, v158, v159
	v_cvt_pk_bf16_f32 v155, v156, v157
	v_add_co_u32_e32 v156, vcc, s0, v146
	s_nop 1
	v_addc_co_u32_e32 v157, vcc, 0, v147, vcc
	global_store_dwordx4 v[156:157], v[152:155], off sc1
	v_pk_mul_f32 v[156:157], v[144:145], v[2:3] op_sel_hi:[0,1]
	s_nop 0
	v_pk_mul_f32 v[154:155], v[144:145], v[6:7] op_sel_hi:[0,1]
	v_pk_mul_f32 v[152:153], v[144:145], v[4:5] op_sel_hi:[0,1]
	v_pk_mul_f32 v[144:145], v[144:145], v[0:1] op_sel_hi:[0,1]
	v_cvt_pk_bf16_f32 v152, v152, v153
	v_cvt_pk_bf16_f32 v153, v154, v155
	v_cvt_pk_bf16_f32 v154, v144, v145
	v_add_co_u32_e32 v144, vcc, 0x2d000, v146
	v_cvt_pk_bf16_f32 v155, v156, v157
	s_nop 1
	v_addc_co_u32_e32 v145, vcc, 0, v147, vcc
	global_store_dwordx4 v[144:145], v[152:155], off sc1

.LBB0_195:
	v_lshl_add_u32 v146, s64, 8, v37
	v_lshl_or_b32 v144, s62, 8, v149
	v_ashrrev_i32_e32 v147, 31, v146
	v_readlane_b32 s26, v252, 5
	v_ashrrev_i32_e32 v145, 31, v144
	v_lshlrev_b64 v[152:153], 11, v[146:147]
	v_readlane_b32 s27, v252, 6
	v_lshlrev_b64 v[154:155], 1, v[144:145]
	v_cvt_pk_bf16_f32 v130, v130, v131
	v_cvt_pk_bf16_f32 v131, v132, v133
	v_cvt_pk_bf16_f32 v132, v126, v127
	v_cvt_pk_bf16_f32 v133, v128, v129
	s_nop 0
	v_lshl_add_u64 v[152:153], s[26:27], 0, v[152:153]
	v_lshl_add_u64 v[144:145], v[152:153], 0, v[154:155]
	global_store_dwordx4 v[144:145], v[130:133], off sc1
	v_cvt_pk_bf16_f32 v118, v118, v119
	v_cvt_pk_bf16_f32 v119, v120, v121
	v_cvt_pk_bf16_f32 v120, v110, v111
	v_or_b32_e32 v110, 16, v146
	v_ashrrev_i32_e32 v111, 31, v110
	v_lshlrev_b64 v[110:111], 11, v[110:111]
	v_lshl_add_u64 v[110:111], s[26:27], 0, v[110:111]
	v_cvt_pk_bf16_f32 v121, v112, v113
	global_store_dwordx4 v[144:145], v[118:121], off offset:256 sc1
	s_mov_b32 s0, 0x40000
	s_nop 0
	v_lshl_add_u64 v[118:119], v[110:111], 0, v[154:155]
	v_cvt_pk_bf16_f32 v110, v122, v123
	v_cvt_pk_bf16_f32 v111, v124, v125
	v_cvt_pk_bf16_f32 v112, v114, v115
	v_cvt_pk_bf16_f32 v113, v116, v117
	global_store_dwordx4 v[118:119], v[110:113], off sc1
	v_cvt_pk_bf16_f32 v102, v102, v103
	v_cvt_pk_bf16_f32 v103, v104, v105
	v_cvt_pk_bf16_f32 v104, v94, v95
	v_or_b32_e32 v94, 32, v146
	v_ashrrev_i32_e32 v95, 31, v94
	v_lshlrev_b64 v[94:95], 11, v[94:95]
	v_lshl_add_u64 v[94:95], s[26:27], 0, v[94:95]
	v_cvt_pk_bf16_f32 v105, v96, v97
	global_store_dwordx4 v[118:119], v[102:105], off offset:256 sc1
	s_nop 1
	v_lshl_add_u64 v[102:103], v[94:95], 0, v[154:155]
	v_cvt_pk_bf16_f32 v94, v106, v107
	v_cvt_pk_bf16_f32 v95, v108, v109
	v_cvt_pk_bf16_f32 v96, v98, v99
	v_cvt_pk_bf16_f32 v97, v100, v101
	global_store_dwordx4 v[102:103], v[94:97], off sc1
	v_cvt_pk_bf16_f32 v90, v90, v91
	v_cvt_pk_bf16_f32 v91, v92, v93
	v_cvt_pk_bf16_f32 v92, v82, v83
	v_or_b32_e32 v82, 48, v146
	v_ashrrev_i32_e32 v83, 31, v82
	v_lshlrev_b64 v[82:83], 11, v[82:83]
	v_lshl_add_u64 v[82:83], s[26:27], 0, v[82:83]
	v_cvt_pk_bf16_f32 v93, v84, v85
	global_store_dwordx4 v[102:103], v[90:93], off offset:256 sc1
	s_mov_b64 s[26:27], 0x40000
	s_nop 0
	v_lshl_add_u64 v[90:91], v[82:83], 0, v[154:155]
	v_cvt_pk_bf16_f32 v82, v86, v87
	v_cvt_pk_bf16_f32 v83, v88, v89
	v_cvt_pk_bf16_f32 v84, v78, v79
	v_cvt_pk_bf16_f32 v85, v80, v81
	global_store_dwordx4 v[90:91], v[82:85], off sc1
	v_cvt_pk_bf16_f32 v74, v74, v75
	v_cvt_pk_bf16_f32 v75, v76, v77
	v_cvt_pk_bf16_f32 v76, v70, v71
	v_cvt_pk_bf16_f32 v77, v72, v73
	global_store_dwordx4 v[90:91], v[74:77], off offset:256 sc1
	v_cvt_pk_bf16_f32 v66, v66, v67
	v_cvt_pk_bf16_f32 v67, v68, v69
	v_cvt_pk_bf16_f32 v68, v62, v63
	v_add_co_u32_e32 v62, vcc, s0, v144
	v_lshl_add_u64 v[70:71], v[144:145], 0, s[26:27]
	s_nop 0
	v_addc_co_u32_e32 v63, vcc, 0, v145, vcc
	s_mov_b32 s0, 0x48000
	v_cvt_pk_bf16_f32 v69, v64, v65
	global_store_dwordx4 v[62:63], v[66:69], off sc1
	v_cvt_pk_bf16_f32 v54, v54, v55
	v_cvt_pk_bf16_f32 v55, v56, v57
	v_cvt_pk_bf16_f32 v56, v46, v47
	v_cvt_pk_bf16_f32 v57, v48, v49
	global_store_dwordx4 v[70:71], v[54:57], off offset:256 sc1
	s_mov_b64 s[26:27], 0x48000
	v_cvt_pk_bf16_f32 v46, v58, v59
	v_cvt_pk_bf16_f32 v47, v60, v61
	v_cvt_pk_bf16_f32 v48, v50, v51
	v_add_co_u32_e32 v50, vcc, s0, v144
	v_lshl_add_u64 v[54:55], v[144:145], 0, s[26:27]
	s_nop 0
	v_addc_co_u32_e32 v51, vcc, 0, v145, vcc
	s_mov_b32 s0, 0x50000
	v_cvt_pk_bf16_f32 v49, v52, v53
	global_store_dwordx4 v[50:51], v[46:49], off sc1
	v_cvt_pk_bf16_f32 v38, v38, v39
	v_cvt_pk_bf16_f32 v39, v40, v41
	v_cvt_pk_bf16_f32 v40, v24, v25
	v_cvt_pk_bf16_f32 v41, v26, v27
	global_store_dwordx4 v[54:55], v[38:41], off offset:256 sc1
	s_mov_b64 s[26:27], 0x50000
	v_cvt_pk_bf16_f32 v24, v42, v43
	v_cvt_pk_bf16_f32 v25, v44, v45
	v_cvt_pk_bf16_f32 v26, v28, v29
	v_add_co_u32_e32 v28, vcc, s0, v144
	v_lshl_add_u64 v[38:39], v[144:145], 0, s[26:27]
	s_nop 0
	v_addc_co_u32_e32 v29, vcc, 0, v145, vcc
	s_mov_b32 s0, 0x58000
	v_cvt_pk_bf16_f32 v27, v30, v31
	global_store_dwordx4 v[28:29], v[24:27], off sc1
	v_cvt_pk_bf16_f32 v16, v16, v17
	v_cvt_pk_bf16_f32 v17, v18, v19
	v_cvt_pk_bf16_f32 v18, v8, v9
	v_cvt_pk_bf16_f32 v19, v10, v11
	global_store_dwordx4 v[38:39], v[16:19], off offset:256 sc1
	s_mov_b64 s[26:27], 0x58000
	v_cvt_pk_bf16_f32 v8, v20, v21
	v_cvt_pk_bf16_f32 v9, v22, v23
	v_cvt_pk_bf16_f32 v10, v12, v13
	v_add_co_u32_e32 v12, vcc, s0, v144
	v_lshl_add_u64 v[16:17], v[144:145], 0, s[26:27]
	s_nop 0
	v_addc_co_u32_e32 v13, vcc, 0, v145, vcc
	v_cvt_pk_bf16_f32 v11, v14, v15
	global_store_dwordx4 v[12:13], v[8:11], off sc1
	v_cvt_pk_bf16_f32 v4, v4, v5
	v_cvt_pk_bf16_f32 v5, v6, v7
	v_cvt_pk_bf16_f32 v6, v0, v1
	v_cvt_pk_bf16_f32 v7, v2, v3
	global_store_dwordx4 v[16:17], v[4:7], off offset:256 sc1
	s_andn2_b64 vcc, exec, s[46:47]
	s_mov_b64 s[26:27], -1
	s_cbranch_vccnz .LBB0_180
